# baseline (speedup 1.0000x reference)
; __device__ __forceinline__ float bf2f(bh v) { return __uint_as_float(((unsigned)v) << 16); }
; __device__ __forceinline__ bh f2bf(float f) { return (bh)(cvtpk(f, 0.f) & 0xffffu); }
; __device__ __forceinline__ void prep1_phase(const Params& p, int l, int L, bh* __restrict__ U, bh* __restrict__ kb, bh* __restrict__ xc, float* __restrict__ dtb, unsigned* __restrict__ bnd) {
;     ...
;     for (int hh = 0; hh < 10; ++hh) {
;       const float v = bf2f(Ur[UC_DQ + hh * 64 + lane]);
;       const float ss = wave_sum(v * v);
;       const float gsc = hh < 8 ? gq[lane] : gk[lane];
;       const float vn = v * rsqrtf(ss * (1.f / 64.f) + EPS) * gsc;
;       const float pr = xor16(vn, lane);
;       float c, s; cossin(lane < 32 ? (pos >> 6) : (pos & 63), lane & 15, c, s);
;       const float o = (lane & 16) ? (vn * c + pr * s) : (vn * c - pr * s);
;       Ur[UC_DQ + hh * 64 + lane] = f2bf(o);
;     }
;     {
;       float v[6]; float ss = 0.f;
; #pragma unroll
;       for (int i = 0; i < 6; ++i) { v[i] = bf2f(Ur[UC_CQ + i * 64 + lane]); ss += v[i] * v[i]; }
;       ss = wave_sum(ss);
;       const float r = rsqrtf(ss * (1.f / 384.f) + EPS);
; #pragma unroll
;       for (int i = 0; i < 6; ++i) Ur[UC_CQ + i * 64 + lane] = f2bf(v[i] * r * qn[i * 64 + lane]);
;       float w[4]; ss = 0.f;
; #pragma unroll
;       for (int i = 0; i < 4; ++i) { w[i] = bf2f(Ur[UC_CKV + i * 64 + lane]); ss += w[i] * w[i]; }
;       ss = wave_sum(ss);
;       const float r2 = rsqrtf(ss * (1.f / 256.f) + EPS);
; #pragma unroll
;       for (int i = 0; i < 4; ++i) Ur[UC_CKV + i * 64 + lane] = f2bf(w[i] * r2 * kvn[i * 64 + lane]);
;       const float kv = bf2f(Ur[UC_KR + (lane & 31)]);
.LBB0_259:
	v_mov_b32_e32 v242, v244
	v_mov_b32_e32 v243, v245
	global_load_ushort v244, v[98:99], off offset:128
	global_load_ushort v245, v[98:99], off offset:256
	s_cmp_lt_u32 s33, 8
	s_cselect_b64 s[44:45], -1, 0
	s_add_i32 s33, s33, 2
	s_cmp_lg_u32 s33, 10
	v_lshlrev_b32_e32 v242, 16, v242
	v_mul_f32_e32 v139, v242, v242
	s_nop 1
	v_mov_b32_dpp v139, v139 quad_perm:[1,0,3,2] row_mask:0xf bank_mask:0xf bound_ctrl:1
	v_fmac_f32_e32 v139, v242, v242
	s_nop 1
	v_add_f32_dpp v139, v139, v139 quad_perm:[2,3,0,1] row_mask:0xf bank_mask:0xf bound_ctrl:1
	s_nop 1
	v_add_f32_dpp v139, v139, v139 row_half_mirror row_mask:0xf bank_mask:0xf bound_ctrl:1
	s_nop 1
	v_add_f32_dpp v139, v139, v139 row_mirror row_mask:0xf bank_mask:0xf bound_ctrl:1
	v_mov_b32_e32 v140, v139
	s_nop 1
	v_permlane16_swap_b32_e32 v139, v140
	v_add_f32_e32 v139, v139, v140
	v_mov_b32_e32 v140, v139
	s_nop 1
	v_permlane32_swap_b32_e32 v139, v140
	v_add_f32_e32 v139, v139, v140
	v_cndmask_b32_e64 v140, v240, v239, s[44:45]
	v_fmamk_f32 v139, v139, 0x3c800000, v189
	v_cmp_gt_f32_e32 vcc, s52, v139
	v_mul_f32_e32 v141, 0x4b800000, v139
	s_nop 0
	v_cndmask_b32_e32 v139, v139, v141, vcc
	v_rsq_f32_e32 v139, v139
	s_nop 0
	v_mul_f32_e32 v141, 0x45800000, v139
	v_cndmask_b32_e32 v139, v139, v141, vcc
	v_mul_f32_e32 v242, v139, v242
	v_mul_f32_e32 v242, v140, v242
	v_mov_b32_e32 v139, v242
	v_mov_b32_e32 v141, v242
	s_nop 1
	v_permlane16_swap_b32_e32 v139, v141
	v_cndmask_b32_e64 v139, v139, v141, s[2:3]
	v_mul_f32_e32 v139, v137, v139
	v_cndmask_b32_e64 v139, v139, -v139, s[2:3]
	v_fmac_f32_e32 v139, v71, v242
	v_cvt_pk_bf16_f32 v242, v139, v177
	global_store_short v[98:99], v242, off offset:-128
	v_lshlrev_b32_e32 v243, 16, v243
	v_mul_f32_e32 v139, v243, v243
	s_nop 1
	v_mov_b32_dpp v139, v139 quad_perm:[1,0,3,2] row_mask:0xf bank_mask:0xf bound_ctrl:1
	v_fmac_f32_e32 v139, v243, v243
	s_nop 1
	v_add_f32_dpp v139, v139, v139 quad_perm:[2,3,0,1] row_mask:0xf bank_mask:0xf bound_ctrl:1
	s_nop 1
	v_add_f32_dpp v139, v139, v139 row_half_mirror row_mask:0xf bank_mask:0xf bound_ctrl:1
	s_nop 1
	v_add_f32_dpp v139, v139, v139 row_mirror row_mask:0xf bank_mask:0xf bound_ctrl:1
	v_mov_b32_e32 v141, v139
	s_nop 1
	v_permlane16_swap_b32_e32 v139, v141
	v_add_f32_e32 v139, v139, v141
	v_mov_b32_e32 v141, v139
	s_nop 1
	v_permlane32_swap_b32_e32 v139, v141
	v_add_f32_e32 v139, v139, v141
	v_fmamk_f32 v139, v139, 0x3c800000, v189
	v_cmp_gt_f32_e32 vcc, s52, v139
	v_mul_f32_e32 v141, 0x4b800000, v139
	s_nop 0
	v_cndmask_b32_e32 v139, v139, v141, vcc
	v_rsq_f32_e32 v139, v139
	s_nop 0
	v_mul_f32_e32 v141, 0x45800000, v139
	v_cndmask_b32_e32 v139, v139, v141, vcc
	v_mul_f32_e32 v243, v139, v243
	v_mul_f32_e32 v243, v140, v243
	v_mov_b32_e32 v139, v243
	v_mov_b32_e32 v140, v243
	s_nop 1
	v_permlane16_swap_b32_e32 v139, v140
	v_cndmask_b32_e64 v139, v139, v140, s[2:3]
	v_mul_f32_e32 v139, v137, v139
	v_cndmask_b32_e64 v139, v139, -v139, s[2:3]
	v_fmac_f32_e32 v139, v71, v243
	v_cvt_pk_bf16_f32 v243, v139, v177
	global_store_short v[98:99], v243, off
	v_lshl_add_u64 v[98:99], v[98:99], 0, s[78:79]
	s_waitcnt vmcnt(2)
	s_cbranch_scc1 .LBB0_259
	global_load_ushort v71, v[72:73], off offset:3072
	global_load_ushort v98, v[72:73], off offset:3200
	global_load_ushort v137, v[72:73], off offset:3328
	global_load_ushort v138, v[72:73], off offset:3456
	global_load_ushort v139, v[72:73], off offset:3584
	global_load_ushort v140, v[72:73], off offset:3712
	s_movk_i32 s33, 0x1000
	v_cmp_lt_i32_e64 s[42:43], 0, v136
	global_load_ushort v76, v[72:73], off offset:3840
	global_load_ushort v77, v[72:73], off offset:3968
	v_add_co_u32_e32 v74, vcc, s33, v72
	v_mov_b32_e32 v82, v70
	v_mov_b32_e32 v83, 0
	v_addc_co_u32_e32 v75, vcc, 0, v73, vcc
	v_lshl_add_u64 v[80:81], v[96:97], 0, v[82:83]
	global_load_ushort v78, v[74:75], off
	global_load_ushort v79, v[74:75], off offset:128
	v_add_co_u32_e32 v80, vcc, s33, v80
	global_load_ushort v186, v[74:75], off offset:2880
	s_nop 1
	v_addc_co_u32_e32 v81, vcc, 0, v81, vcc
	global_load_ushort v84, v[80:81], off offset:256
	s_waitcnt vmcnt(11)
	v_lshlrev_b32_e32 v71, 16, v71
	s_waitcnt vmcnt(10)
	v_lshlrev_b32_e32 v98, 16, v98
	v_mul_f32_e32 v99, v98, v98
	v_fmac_f32_e32 v99, v71, v71
	s_waitcnt vmcnt(9)
	v_lshlrev_b32_e32 v137, 16, v137
	v_fmac_f32_e32 v99, v137, v137
	s_waitcnt vmcnt(8)
	v_lshlrev_b32_e32 v138, 16, v138
	v_fmac_f32_e32 v99, v138, v138
	s_waitcnt vmcnt(7)
	v_lshlrev_b32_e32 v139, 16, v139
	v_fmac_f32_e32 v99, v139, v139
	s_waitcnt vmcnt(6)
	v_lshlrev_b32_e32 v140, 16, v140
	v_fmac_f32_e32 v99, v140, v140
	s_nop 1
	v_add_f32_dpp v99, v99, v99 quad_perm:[1,0,3,2] row_mask:0xf bank_mask:0xf bound_ctrl:1
	s_nop 1
	v_add_f32_dpp v99, v99, v99 quad_perm:[2,3,0,1] row_mask:0xf bank_mask:0xf bound_ctrl:1
	s_nop 1
	v_add_f32_dpp v99, v99, v99 row_half_mirror row_mask:0xf bank_mask:0xf bound_ctrl:1
	s_nop 1
	v_add_f32_dpp v99, v99, v99 row_mirror row_mask:0xf bank_mask:0xf bound_ctrl:1
	v_mov_b32_e32 v141, v99
	s_nop 1
	v_permlane16_swap_b32_e32 v99, v141
	v_add_f32_e32 v99, v99, v141
	v_mov_b32_e32 v141, v99
	s_nop 1
	v_permlane32_swap_b32_e32 v99, v141
	v_add_f32_e32 v99, v99, v141
	v_fmamk_f32 v99, v99, 0x3b2aaaab, v189
	v_cmp_gt_f32_e32 vcc, s52, v99
	v_mul_f32_e32 v141, 0x4b800000, v99
	s_nop 0
	v_cndmask_b32_e32 v99, v99, v141, vcc
	v_rsq_f32_e32 v99, v99
	s_nop 0
	v_mul_f32_e32 v141, 0x45800000, v99
	v_cndmask_b32_e32 v99, v99, v141, vcc
	v_mul_f32_e32 v71, v99, v71
	v_mul_f32_e32 v71, v182, v71
	v_cvt_pk_bf16_f32 v71, v71, v177
	global_store_short v[72:73], v71, off offset:3072
	v_mul_f32_e32 v71, v99, v98
	v_mul_f32_e32 v71, v183, v71
	v_cvt_pk_bf16_f32 v71, v71, v177
	global_store_short v[72:73], v71, off offset:3200
	v_mul_f32_e32 v71, v99, v137
	v_mul_f32_e32 v71, v184, v71
	v_cvt_pk_bf16_f32 v71, v71, v177
	global_store_short v[72:73], v71, off offset:3328
	v_mul_f32_e32 v71, v99, v138
	v_mul_f32_e32 v71, v185, v71
	v_cvt_pk_bf16_f32 v71, v71, v177
	global_store_short v[72:73], v71, off offset:3456
	v_mul_f32_e32 v71, v99, v139
	v_mul_f32_e32 v71, v71, v232
	v_cvt_pk_bf16_f32 v71, v71, v177
	global_store_short v[72:73], v71, off offset:3584
	v_mul_f32_e32 v71, v99, v140
	v_mul_f32_e32 v71, v71, v233
	v_cvt_pk_bf16_f32 v71, v71, v177
	global_store_short v[72:73], v71, off offset:3712
	s_waitcnt vmcnt(6)
; __device__ __forceinline__ float bf2f(bh v) { return __uint_as_float(((unsigned)v) << 16); }
; __device__ __forceinline__ bh f2bf(float f) { return (bh)(cvtpk(f, 0.f) & 0xffffu); }
; __device__ __forceinline__ float silu_f(float x) { return x / (1.f + __expf(-x)); }
; __device__ __forceinline__ void prep1_phase(const Params& p, int l, int L, bh* __restrict__ U, bh* __restrict__ kb, bh* __restrict__ xc, float* __restrict__ dtb, unsigned* __restrict__ bnd) {
;     ...
;       float w[4]; ss = 0.f;
; #pragma unroll
;       for (int i = 0; i < 4; ++i) { w[i] = bf2f(Ur[UC_CKV + i * 64 + lane]); ss += w[i] * w[i]; }
;       ss = wave_sum(ss);
;       const float r2 = rsqrtf(ss * (1.f / 256.f) + EPS);
; #pragma unroll
;       for (int i = 0; i < 4; ++i) Ur[UC_CKV + i * 64 + lane] = f2bf(w[i] * r2 * kvn[i * 64 + lane]);
;       const float kv = bf2f(Ur[UC_KR + (lane & 31)]);
;       const float pr = xor16(kv, lane);
;       float c, s; cossin(pos, lane & 15, c, s);
;       float o = (lane & 16) ? (kv * c + pr * s) : (kv * c - pr * s);
;       if (lane >= 32) o = 0.f;
;       const bh ob = f2bf(o);
; #pragma unroll
;       for (int h = 0; h < 4; ++h) kb[(long)t * 512 + h * 128 + 64 + lane] = ob;
;     }
;     {
;       const bool hasL = pos > 0, hasR = pos < L - 1;
; #pragma unroll
;       for (int i = 0; i < 12; ++i) {
;         const int c = i * 64 + lane;
;         float a = cbias[c] + cw[768 + c] * bf2f(Ur[UC_XBC + c]);
;         if (hasL) a += cw[c] * bf2f(Ur[UC_XBC + c - UW]);
;         if (hasR) a += cw[2 * 768 + c] * bf2f(Ur[UC_XBC + c + UW]);
;         xc[(long)t * 768 + c] = f2bf(silu_f(a));
	v_mov_b32_e32 v71, v76
	s_nop 0
	v_mov_b32_e32 v98, v77
	v_lshlrev_b32_e32 v71, 16, v71
	v_lshlrev_b32_e32 v137, 16, v98
	v_add_co_u32_e32 v98, vcc, s33, v72
	v_mul_f32_e32 v138, v137, v137
	s_nop 0
	v_addc_co_u32_e32 v99, vcc, 0, v73, vcc
	v_mov_b32_e32 v139, v78
	v_mov_b32_e32 v140, v79
	v_fmac_f32_e32 v138, v71, v71
	v_lshlrev_b32_e32 v139, 16, v139
	v_fmac_f32_e32 v138, v139, v139
	v_lshlrev_b32_e32 v140, 16, v140
	v_fmac_f32_e32 v138, v140, v140
	s_nop 1
	v_add_f32_dpp v138, v138, v138 quad_perm:[1,0,3,2] row_mask:0xf bank_mask:0xf bound_ctrl:1
	s_nop 1
	v_add_f32_dpp v138, v138, v138 quad_perm:[2,3,0,1] row_mask:0xf bank_mask:0xf bound_ctrl:1
	s_nop 1
	v_add_f32_dpp v138, v138, v138 row_half_mirror row_mask:0xf bank_mask:0xf bound_ctrl:1
	s_nop 1
	v_add_f32_dpp v138, v138, v138 row_mirror row_mask:0xf bank_mask:0xf bound_ctrl:1
	v_mov_b32_e32 v141, v138
	s_nop 1
	v_permlane16_swap_b32_e32 v138, v141
	v_add_f32_e32 v138, v138, v141
	v_mov_b32_e32 v141, v138
	s_nop 1
	v_permlane32_swap_b32_e32 v138, v141
	v_add_f32_e32 v138, v138, v141
	v_fmamk_f32 v138, v138, 0x3b800000, v189
	v_cmp_gt_f32_e32 vcc, s52, v138
	v_mul_f32_e32 v141, 0x4b800000, v138
	s_nop 0
	v_cndmask_b32_e32 v138, v138, v141, vcc
	v_rsq_f32_e32 v138, v138
	s_nop 0
	v_mul_f32_e32 v141, 0x45800000, v138
	v_cndmask_b32_e32 v138, v138, v141, vcc
	v_mul_f32_e32 v71, v138, v71
	v_mul_f32_e32 v71, v234, v71
	v_cvt_pk_bf16_f32 v71, v71, v177
	global_store_short v[72:73], v71, off offset:3840
	v_mul_f32_e32 v71, v138, v137
	v_mul_f32_e32 v71, v235, v71
	v_cvt_pk_bf16_f32 v71, v71, v177
	global_store_short v[72:73], v71, off offset:3968
	v_mul_f32_e32 v71, v138, v139
	v_mul_f32_e32 v71, v238, v71
	v_cvt_pk_bf16_f32 v71, v71, v177
	global_store_short v[98:99], v71, off
	v_mul_f32_e32 v71, v138, v140
	v_mul_f32_e32 v71, v241, v71
	v_cvt_pk_bf16_f32 v71, v71, v177
	global_store_short v[98:99], v71, off offset:128
	v_mov_b32_e32 v71, v177
	v_lshl_add_u64 v[96:97], v[96:97], 0, v[70:71]
	v_add_co_u32_e32 v96, vcc, s33, v96
	s_nop 1
	v_addc_co_u32_e32 v97, vcc, 0, v97, vcc
	v_mov_b32_e32 v71, v84
	v_lshlrev_b32_e32 v71, 16, v71
	v_mov_b32_e32 v96, v71
	v_mov_b32_e32 v97, v71
	s_nop 1
	v_permlane16_swap_b32_e32 v96, v97
	v_cndmask_b32_e64 v137, v96, v97, s[2:3]
	v_cvt_f64_i32_e32 v[96:97], v136
	v_mul_f64 v[138:139], v[4:5], v[96:97]
	v_floor_f64_e32 v[138:139], v[138:139]
	v_fma_f64 v[96:97], v[4:5], v[96:97], -v[138:139]
	v_cvt_f32_f64_e32 v96, v[96:97]
	v_cos_f32_e32 v97, v96
	v_sin_f32_e32 v96, v96
	s_nop 0
	v_mul_f32_e32 v96, v96, v137
	v_cndmask_b32_e64 v96, v96, -v96, s[2:3]
	v_fmac_f32_e32 v96, v97, v71
	v_cndmask_b32_e64 v71, v96, 0, s[6:7]
	v_lshlrev_b64 v[96:97], 10, v[2:3]
	v_cvt_pk_bf16_f32 v71, v71, v177
	v_lshl_add_u64 v[96:97], v[16:17], 0, v[96:97]
	global_store_short v[96:97], v71, off offset:128
	global_store_short v[96:97], v71, off offset:384
	global_store_short v[96:97], v71, off offset:640
	global_store_short v[96:97], v71, off offset:896
	v_readlane_b32 s33, v253, 53
	v_mov_b32_e32 v138, 0xffffde00
	v_mov_b32_e32 v140, 0x2200
	v_mov_b32_e32 v141, 0
	v_cndmask_b32_e64 v138, 0, v138, s[42:43]
	v_cmp_gt_i32_e64 s[44:45], s33, v136
	v_ashrrev_i32_e32 v139, 31, v138
	v_lshl_add_u64 v[138:139], v[98:99], 0, v[138:139]
	v_mad_i64_i32 v[236:237], s[52:53], v2, s74, v[66:67]
	v_cndmask_b32_e64 v140, 0, v140, s[44:45]
	s_nop 0
	v_lshl_add_u64 v[140:141], v[98:99], 0, v[140:141]
	global_load_ushort v74, v[98:99], off offset:1344
	global_load_ushort v75, v[98:99], off offset:1472
	global_load_ushort v76, v[98:99], off offset:1600
	global_load_ushort v77, v[98:99], off offset:1728
	global_load_ushort v78, v[98:99], off offset:1856
	global_load_ushort v79, v[98:99], off offset:1984
	global_load_ushort v80, v[98:99], off offset:2112
	global_load_ushort v81, v[98:99], off offset:2240
	global_load_ushort v82, v[98:99], off offset:2368
	global_load_ushort v83, v[98:99], off offset:2496
	global_load_ushort v84, v[98:99], off offset:2624
	global_load_ushort v85, v[98:99], off offset:2752
	global_load_ushort v86, v[138:139], off offset:1344
	global_load_ushort v87, v[138:139], off offset:1472
	global_load_ushort v88, v[138:139], off offset:1600
	global_load_ushort v89, v[138:139], off offset:1728
	global_load_ushort v90, v[138:139], off offset:1856
	global_load_ushort v91, v[138:139], off offset:1984
	global_load_ushort v92, v[138:139], off offset:2112
	global_load_ushort v93, v[138:139], off offset:2240
	global_load_ushort v94, v[138:139], off offset:2368
	global_load_ushort v95, v[138:139], off offset:2496
	global_load_ushort v96, v[138:139], off offset:2624
	global_load_ushort v97, v[138:139], off offset:2752
	global_load_ushort v142, v[140:141], off offset:1344
	global_load_ushort v143, v[140:141], off offset:1472
	global_load_ushort v144, v[140:141], off offset:1600
	global_load_ushort v145, v[140:141], off offset:1728
	global_load_ushort v146, v[140:141], off offset:1856
	global_load_ushort v147, v[140:141], off offset:1984
	global_load_ushort v148, v[140:141], off offset:2112
	global_load_ushort v149, v[140:141], off offset:2240
	global_load_ushort v150, v[140:141], off offset:2368
	global_load_ushort v151, v[140:141], off offset:2496
	global_load_ushort v152, v[140:141], off offset:2624
	global_load_ushort v153, v[140:141], off offset:2752
	s_waitcnt vmcnt(11)
; __device__ __forceinline__ float bf2f(bh v) { return __uint_as_float(((unsigned)v) << 16); }
; __device__ __forceinline__ bh f2bf(float f) { return (bh)(cvtpk(f, 0.f) & 0xffffu); }
; __device__ __forceinline__ float silu_f(float x) { return x / (1.f + __expf(-x)); }
; __device__ __forceinline__ void prep1_phase(const Params& p, int l, int L, bh* __restrict__ U, bh* __restrict__ kb, bh* __restrict__ xc, float* __restrict__ dtb, unsigned* __restrict__ bnd) {
;     ...
;       const bool hasL = pos > 0, hasR = pos < L - 1;
; #pragma unroll
;       for (int i = 0; i < 12; ++i) {
;         const int c = i * 64 + lane;
;         float a = cbias[c] + cw[768 + c] * bf2f(Ur[UC_XBC + c]);
;         if (hasL) a += cw[c] * bf2f(Ur[UC_XBC + c - UW]);
;         if (hasR) a += cw[2 * 768 + c] * bf2f(Ur[UC_XBC + c + UW]);
;         xc[(long)t * 768 + c] = f2bf(silu_f(a));
;       }
	v_lshlrev_b32_e32 v98, 16, v74
	v_fma_f32 v71, v208, v98, v154
	v_lshlrev_b32_e32 v98, 16, v86
	v_lshlrev_b32_e32 v99, 16, v142
	v_cndmask_b32_e64 v98, 0, v98, s[42:43]
	v_cndmask_b32_e64 v99, 0, v99, s[44:45]
	v_fmac_f32_e32 v71, v166, v98
	v_fmac_f32_e32 v71, v220, v99
	v_mul_f32_e32 v98, 0xbfb8aa3b, v71
	v_exp_f32_e32 v98, v98
	s_nop 0
	v_add_f32_e32 v99, 1.0, v98
	v_div_scale_f32 v98, s[52:53], v99, v99, v71
	v_rcp_f32_e32 v137, v98
	v_div_scale_f32 v136, vcc, v71, v99, v71
	v_fma_f32 v139, -v98, v137, 1.0
	v_fmac_f32_e32 v137, v139, v137
	v_mul_f32_e32 v139, v136, v137
	v_fma_f32 v140, -v98, v139, v136
	v_fmac_f32_e32 v139, v140, v137
	v_fma_f32 v98, -v98, v139, v136
	v_div_fmas_f32 v136, v98, v137, v139
	v_div_fixup_f32 v71, v136, v99, v71
	v_cvt_pk_bf16_f32 v71, v71, v177
	global_store_short v[236:237], v71, off offset:0
	s_waitcnt vmcnt(11)
	v_lshlrev_b32_e32 v98, 16, v75
	v_fma_f32 v71, v209, v98, v155
	v_lshlrev_b32_e32 v98, 16, v87
	v_lshlrev_b32_e32 v99, 16, v143
	v_cndmask_b32_e64 v98, 0, v98, s[42:43]
	v_cndmask_b32_e64 v99, 0, v99, s[44:45]
	v_fmac_f32_e32 v71, v167, v98
	v_fmac_f32_e32 v71, v221, v99
	v_mul_f32_e32 v98, 0xbfb8aa3b, v71
	v_exp_f32_e32 v98, v98
	s_nop 0
	v_add_f32_e32 v99, 1.0, v98
	v_div_scale_f32 v98, s[52:53], v99, v99, v71
	v_rcp_f32_e32 v137, v98
	v_div_scale_f32 v136, vcc, v71, v99, v71
	v_fma_f32 v139, -v98, v137, 1.0
	v_fmac_f32_e32 v137, v139, v137
	v_mul_f32_e32 v139, v136, v137
	v_fma_f32 v140, -v98, v139, v136
	v_fmac_f32_e32 v139, v140, v137
	v_fma_f32 v98, -v98, v139, v136
	v_div_fmas_f32 v136, v98, v137, v139
	v_div_fixup_f32 v71, v136, v99, v71
	v_cvt_pk_bf16_f32 v71, v71, v177
	global_store_short v[236:237], v71, off offset:128
	s_waitcnt vmcnt(11)
	v_lshlrev_b32_e32 v98, 16, v76
	v_fma_f32 v71, v210, v98, v156
	v_lshlrev_b32_e32 v98, 16, v88
	v_lshlrev_b32_e32 v99, 16, v144
	v_cndmask_b32_e64 v98, 0, v98, s[42:43]
	v_cndmask_b32_e64 v99, 0, v99, s[44:45]
	v_fmac_f32_e32 v71, v168, v98
	v_fmac_f32_e32 v71, v222, v99
	v_mul_f32_e32 v98, 0xbfb8aa3b, v71
	v_exp_f32_e32 v98, v98
	s_nop 0
	v_add_f32_e32 v99, 1.0, v98
	v_div_scale_f32 v98, s[52:53], v99, v99, v71
	v_rcp_f32_e32 v137, v98
	v_div_scale_f32 v136, vcc, v71, v99, v71
	v_fma_f32 v139, -v98, v137, 1.0
	v_fmac_f32_e32 v137, v139, v137
	v_mul_f32_e32 v139, v136, v137
	v_fma_f32 v140, -v98, v139, v136
	v_fmac_f32_e32 v139, v140, v137
	v_fma_f32 v98, -v98, v139, v136
	v_div_fmas_f32 v136, v98, v137, v139
	v_div_fixup_f32 v71, v136, v99, v71
	v_cvt_pk_bf16_f32 v71, v71, v177
	global_store_short v[236:237], v71, off offset:256
	s_waitcnt vmcnt(11)
	v_lshlrev_b32_e32 v98, 16, v77
	v_fma_f32 v71, v211, v98, v157
	v_lshlrev_b32_e32 v98, 16, v89
	v_lshlrev_b32_e32 v99, 16, v145
	v_cndmask_b32_e64 v98, 0, v98, s[42:43]
	v_cndmask_b32_e64 v99, 0, v99, s[44:45]
	v_fmac_f32_e32 v71, v169, v98
	v_fmac_f32_e32 v71, v223, v99
	v_mul_f32_e32 v98, 0xbfb8aa3b, v71
	v_exp_f32_e32 v98, v98
	s_nop 0
	v_add_f32_e32 v99, 1.0, v98
	v_div_scale_f32 v98, s[52:53], v99, v99, v71
	v_rcp_f32_e32 v137, v98
	v_div_scale_f32 v136, vcc, v71, v99, v71
	v_fma_f32 v139, -v98, v137, 1.0
	v_fmac_f32_e32 v137, v139, v137
	v_mul_f32_e32 v139, v136, v137
	v_fma_f32 v140, -v98, v139, v136
	v_fmac_f32_e32 v139, v140, v137
	v_fma_f32 v98, -v98, v139, v136
	v_div_fmas_f32 v136, v98, v137, v139
	v_div_fixup_f32 v71, v136, v99, v71
	v_cvt_pk_bf16_f32 v71, v71, v177
	global_store_short v[236:237], v71, off offset:384
	s_waitcnt vmcnt(11)
	v_lshlrev_b32_e32 v98, 16, v78
	v_fma_f32 v71, v212, v98, v158
	v_lshlrev_b32_e32 v98, 16, v90
	v_lshlrev_b32_e32 v99, 16, v146
	v_cndmask_b32_e64 v98, 0, v98, s[42:43]
	v_cndmask_b32_e64 v99, 0, v99, s[44:45]
	v_fmac_f32_e32 v71, v170, v98
	v_fmac_f32_e32 v71, v224, v99
	v_mul_f32_e32 v98, 0xbfb8aa3b, v71
	v_exp_f32_e32 v98, v98
	s_nop 0
	v_add_f32_e32 v99, 1.0, v98
	v_div_scale_f32 v98, s[52:53], v99, v99, v71
	v_rcp_f32_e32 v137, v98
	v_div_scale_f32 v136, vcc, v71, v99, v71
	v_fma_f32 v139, -v98, v137, 1.0
	v_fmac_f32_e32 v137, v139, v137
	v_mul_f32_e32 v139, v136, v137
	v_fma_f32 v140, -v98, v139, v136
	v_fmac_f32_e32 v139, v140, v137
	v_fma_f32 v98, -v98, v139, v136
	v_div_fmas_f32 v136, v98, v137, v139
	v_div_fixup_f32 v71, v136, v99, v71
	v_cvt_pk_bf16_f32 v71, v71, v177
	global_store_short v[236:237], v71, off offset:512
	s_waitcnt vmcnt(11)
	v_lshlrev_b32_e32 v98, 16, v79
	v_fma_f32 v71, v213, v98, v159
	v_lshlrev_b32_e32 v98, 16, v91
	v_lshlrev_b32_e32 v99, 16, v147
	v_cndmask_b32_e64 v98, 0, v98, s[42:43]
	v_cndmask_b32_e64 v99, 0, v99, s[44:45]
	v_fmac_f32_e32 v71, v171, v98
	v_fmac_f32_e32 v71, v225, v99
	v_mul_f32_e32 v98, 0xbfb8aa3b, v71
	v_exp_f32_e32 v98, v98
	s_nop 0
	v_add_f32_e32 v99, 1.0, v98
	v_div_scale_f32 v98, s[52:53], v99, v99, v71
	v_rcp_f32_e32 v137, v98
	v_div_scale_f32 v136, vcc, v71, v99, v71
	v_fma_f32 v139, -v98, v137, 1.0
	v_fmac_f32_e32 v137, v139, v137
	v_mul_f32_e32 v139, v136, v137
	v_fma_f32 v140, -v98, v139, v136
	v_fmac_f32_e32 v139, v140, v137
	v_fma_f32 v98, -v98, v139, v136
	v_div_fmas_f32 v136, v98, v137, v139
	v_div_fixup_f32 v71, v136, v99, v71
	v_cvt_pk_bf16_f32 v71, v71, v177
	global_store_short v[236:237], v71, off offset:640
	s_waitcnt vmcnt(11)
; __device__ __forceinline__ float bf2f(bh v) { return __uint_as_float(((unsigned)v) << 16); }
; __device__ __forceinline__ bh f2bf(float f) { return (bh)(cvtpk(f, 0.f) & 0xffffu); }
; __device__ __forceinline__ float silu_f(float x) { return x / (1.f + __expf(-x)); }
; __device__ __forceinline__ void prep1_phase(const Params& p, int l, int L, bh* __restrict__ U, bh* __restrict__ kb, bh* __restrict__ xc, float* __restrict__ dtb, unsigned* __restrict__ bnd) {
;     ...
;       const bool hasL = pos > 0, hasR = pos < L - 1;
; #pragma unroll
;       for (int i = 0; i < 12; ++i) {
;         const int c = i * 64 + lane;
;         float a = cbias[c] + cw[768 + c] * bf2f(Ur[UC_XBC + c]);
;         if (hasL) a += cw[c] * bf2f(Ur[UC_XBC + c - UW]);
;         if (hasR) a += cw[2 * 768 + c] * bf2f(Ur[UC_XBC + c + UW]);
;         xc[(long)t * 768 + c] = f2bf(silu_f(a));
;       }
;     }
;     if (lane < 16) {
;       const float raw = bf2f(Ur[UC_DT + lane]) + dtbias[lane];
;       const float e = __builtin_amdgcn_exp2f(raw * LOG2E);
;       const float sp = e < 1.0e-3f ? e * (1.f - 0.5f * e) : __builtin_amdgcn_logf(1.f + e) * 0.6931471805599453f;
;       dtb[(long)t * 16 + lane] = raw > 20.f ? raw : sp;
;     }
	v_lshlrev_b32_e32 v98, 16, v80
	v_fma_f32 v71, v214, v98, v160
	v_lshlrev_b32_e32 v98, 16, v92
	v_lshlrev_b32_e32 v99, 16, v148
	v_cndmask_b32_e64 v98, 0, v98, s[42:43]
	v_cndmask_b32_e64 v99, 0, v99, s[44:45]
	v_fmac_f32_e32 v71, v172, v98
	v_fmac_f32_e32 v71, v226, v99
	v_mul_f32_e32 v98, 0xbfb8aa3b, v71
	v_exp_f32_e32 v98, v98
	s_nop 0
	v_add_f32_e32 v99, 1.0, v98
	v_div_scale_f32 v98, s[52:53], v99, v99, v71
	v_rcp_f32_e32 v137, v98
	v_div_scale_f32 v136, vcc, v71, v99, v71
	v_fma_f32 v139, -v98, v137, 1.0
	v_fmac_f32_e32 v137, v139, v137
	v_mul_f32_e32 v139, v136, v137
	v_fma_f32 v140, -v98, v139, v136
	v_fmac_f32_e32 v139, v140, v137
	v_fma_f32 v98, -v98, v139, v136
	v_div_fmas_f32 v136, v98, v137, v139
	v_div_fixup_f32 v71, v136, v99, v71
	v_cvt_pk_bf16_f32 v71, v71, v177
	global_store_short v[236:237], v71, off offset:768
	s_waitcnt vmcnt(11)
	v_lshlrev_b32_e32 v98, 16, v81
	v_fma_f32 v71, v215, v98, v161
	v_lshlrev_b32_e32 v98, 16, v93
	v_lshlrev_b32_e32 v99, 16, v149
	v_cndmask_b32_e64 v98, 0, v98, s[42:43]
	v_cndmask_b32_e64 v99, 0, v99, s[44:45]
	v_fmac_f32_e32 v71, v173, v98
	v_fmac_f32_e32 v71, v227, v99
	v_mul_f32_e32 v98, 0xbfb8aa3b, v71
	v_exp_f32_e32 v98, v98
	s_nop 0
	v_add_f32_e32 v99, 1.0, v98
	v_div_scale_f32 v98, s[52:53], v99, v99, v71
	v_rcp_f32_e32 v137, v98
	v_div_scale_f32 v136, vcc, v71, v99, v71
	v_fma_f32 v139, -v98, v137, 1.0
	v_fmac_f32_e32 v137, v139, v137
	v_mul_f32_e32 v139, v136, v137
	v_fma_f32 v140, -v98, v139, v136
	v_fmac_f32_e32 v139, v140, v137
	v_fma_f32 v98, -v98, v139, v136
	v_div_fmas_f32 v136, v98, v137, v139
	v_div_fixup_f32 v71, v136, v99, v71
	v_cvt_pk_bf16_f32 v71, v71, v177
	global_store_short v[236:237], v71, off offset:896
	s_waitcnt vmcnt(11)
	v_lshlrev_b32_e32 v98, 16, v82
	v_fma_f32 v71, v216, v98, v162
	v_lshlrev_b32_e32 v98, 16, v94
	v_lshlrev_b32_e32 v99, 16, v150
	v_cndmask_b32_e64 v98, 0, v98, s[42:43]
	v_cndmask_b32_e64 v99, 0, v99, s[44:45]
	v_fmac_f32_e32 v71, v174, v98
	v_fmac_f32_e32 v71, v228, v99
	v_mul_f32_e32 v98, 0xbfb8aa3b, v71
	v_exp_f32_e32 v98, v98
	s_nop 0
	v_add_f32_e32 v99, 1.0, v98
	v_div_scale_f32 v98, s[52:53], v99, v99, v71
	v_rcp_f32_e32 v137, v98
	v_div_scale_f32 v136, vcc, v71, v99, v71
	v_fma_f32 v139, -v98, v137, 1.0
	v_fmac_f32_e32 v137, v139, v137
	v_mul_f32_e32 v139, v136, v137
	v_fma_f32 v140, -v98, v139, v136
	v_fmac_f32_e32 v139, v140, v137
	v_fma_f32 v98, -v98, v139, v136
	v_div_fmas_f32 v136, v98, v137, v139
	v_div_fixup_f32 v71, v136, v99, v71
	v_cvt_pk_bf16_f32 v71, v71, v177
	global_store_short v[236:237], v71, off offset:1024
	s_waitcnt vmcnt(11)
	v_lshlrev_b32_e32 v98, 16, v83
	v_fma_f32 v71, v217, v98, v163
	v_lshlrev_b32_e32 v98, 16, v95
	v_lshlrev_b32_e32 v99, 16, v151
	v_cndmask_b32_e64 v98, 0, v98, s[42:43]
	v_cndmask_b32_e64 v99, 0, v99, s[44:45]
	v_fmac_f32_e32 v71, v175, v98
	v_fmac_f32_e32 v71, v229, v99
	v_mul_f32_e32 v98, 0xbfb8aa3b, v71
	v_exp_f32_e32 v98, v98
	s_nop 0
	v_add_f32_e32 v99, 1.0, v98
	v_div_scale_f32 v98, s[52:53], v99, v99, v71
	v_rcp_f32_e32 v137, v98
	v_div_scale_f32 v136, vcc, v71, v99, v71
	v_fma_f32 v139, -v98, v137, 1.0
	v_fmac_f32_e32 v137, v139, v137
	v_mul_f32_e32 v139, v136, v137
	v_fma_f32 v140, -v98, v139, v136
	v_fmac_f32_e32 v139, v140, v137
	v_fma_f32 v98, -v98, v139, v136
	v_div_fmas_f32 v136, v98, v137, v139
	v_div_fixup_f32 v71, v136, v99, v71
	v_cvt_pk_bf16_f32 v71, v71, v177
	global_store_short v[236:237], v71, off offset:1152
	s_waitcnt vmcnt(11)
	v_lshlrev_b32_e32 v98, 16, v84
	v_fma_f32 v71, v218, v98, v164
	v_lshlrev_b32_e32 v98, 16, v96
	v_lshlrev_b32_e32 v99, 16, v152
	v_cndmask_b32_e64 v98, 0, v98, s[42:43]
	v_cndmask_b32_e64 v99, 0, v99, s[44:45]
	v_fmac_f32_e32 v71, v206, v98
	v_fmac_f32_e32 v71, v230, v99
	v_mul_f32_e32 v98, 0xbfb8aa3b, v71
	v_exp_f32_e32 v98, v98
	s_nop 0
	v_add_f32_e32 v99, 1.0, v98
	v_div_scale_f32 v98, s[52:53], v99, v99, v71
	v_rcp_f32_e32 v137, v98
	v_div_scale_f32 v136, vcc, v71, v99, v71
	v_fma_f32 v139, -v98, v137, 1.0
	v_fmac_f32_e32 v137, v139, v137
	v_mul_f32_e32 v139, v136, v137
	v_fma_f32 v140, -v98, v139, v136
	v_fmac_f32_e32 v139, v140, v137
	v_fma_f32 v98, -v98, v139, v136
	v_div_fmas_f32 v136, v98, v137, v139
	v_div_fixup_f32 v71, v136, v99, v71
	v_cvt_pk_bf16_f32 v71, v71, v177
	global_store_short v[236:237], v71, off offset:1280
	s_waitcnt vmcnt(11)
	v_lshlrev_b32_e32 v98, 16, v85
	v_fma_f32 v71, v219, v98, v165
	v_lshlrev_b32_e32 v98, 16, v97
	v_lshlrev_b32_e32 v99, 16, v153
	v_cndmask_b32_e64 v98, 0, v98, s[42:43]
	v_cndmask_b32_e64 v99, 0, v99, s[44:45]
	v_fmac_f32_e32 v71, v207, v98
	v_fmac_f32_e32 v71, v231, v99
	v_mul_f32_e32 v98, 0xbfb8aa3b, v71
	v_exp_f32_e32 v98, v98
	s_nop 0
	v_add_f32_e32 v99, 1.0, v98
	v_div_scale_f32 v98, s[52:53], v99, v99, v71
	v_rcp_f32_e32 v137, v98
	v_div_scale_f32 v136, vcc, v71, v99, v71
	v_fma_f32 v139, -v98, v137, 1.0
	v_fmac_f32_e32 v137, v139, v137
	v_mul_f32_e32 v139, v136, v137
	v_fma_f32 v140, -v98, v139, v136
	v_fmac_f32_e32 v139, v140, v137
	v_fma_f32 v98, -v98, v139, v136
	v_div_fmas_f32 v136, v98, v137, v139
	v_div_fixup_f32 v71, v136, v99, v71
	v_cvt_pk_bf16_f32 v71, v71, v177
	global_store_short v[236:237], v71, off offset:1408
	s_and_saveexec_b64 s[42:43], s[0:1]
	s_cbranch_execz .LBB0_253
	v_add_co_u32_e32 v72, vcc, 0x1000, v72
	s_mov_b32 s33, 0x3a83126f
	s_nop 0
	v_addc_co_u32_e32 v73, vcc, 0, v73, vcc
	v_mov_b32_e32 v71, v186
	s_nop 0
	v_mov_b32_e32 v72, v187
	v_lshlrev_b32_e32 v71, 16, v71
	v_add_f32_e32 v71, v72, v71
	v_mul_f32_e32 v72, 0x3fb8aa3b, v71
	v_exp_f32_e32 v73, v72
	s_nop 0
	v_cmp_ngt_f32_e32 vcc, s33, v73
	s_and_saveexec_b64 s[44:45], vcc
	s_xor_b64 s[44:45], exec, s[44:45]
	v_add_f32_e32 v72, 1.0, v73
	v_log_f32_e32 v72, v72
	s_nop 0
	v_mul_f32_e32 v72, 0x3f317218, v72
	s_andn2_saveexec_b64 s[44:45], s[44:45]
	s_cbranch_execz .LBB0_252
	v_fma_f32 v72, v73, -0.5, 1.0
	v_mul_f32_e32 v72, v73, v72
	s_branch .LBB0_252
